# grid barrier: all WGs poll the top-level arrival counter directly (drops the TOPGEN/XGEN release hops)
# speedup vs baseline: 1.0512x; 1.0049x over previous
.LBB0_1044:
	s_or_b64 exec, exec, s[12:13]
	v_cvt_f32_u32_e32 v4, v2
	s_waitcnt vmcnt(0)
	v_readfirstlane_b32 s0, v3
	v_sub_u32_e32 v3, 0, v2
	v_rcp_iflag_f32_e32 v4, v4
	v_add_u32_e32 v5, s0, v1
	v_mul_f32_e32 v4, 0x4f7ffffe, v4
	v_cvt_u32_f32_e32 v4, v4
	v_mul_lo_u32 v1, v3, v4
	v_mul_hi_u32 v1, v4, v1
	v_add_u32_e32 v1, v4, v1
	v_mul_hi_u32 v1, v5, v1
	v_mul_lo_u32 v3, v1, v2
	v_sub_u32_e32 v3, v5, v3
	v_add_u32_e32 v4, 1, v1
	v_cmp_ge_u32_e32 vcc, v3, v2
	s_nop 1
	v_cndmask_b32_e32 v1, v1, v4, vcc
	v_sub_u32_e32 v4, v3, v2
	v_cndmask_b32_e32 v3, v3, v4, vcc
	v_add_u32_e32 v4, 1, v1
	v_cmp_ge_u32_e32 vcc, v3, v2
	v_add_u32_e32 v3, 1, v5
	s_nop 0
	v_cndmask_b32_e32 v1, v1, v4, vcc
	v_mul_lo_u32 v4, v2, v1
	v_add_u32_e32 v2, v4, v2
	v_cmp_ne_u32_e32 vcc, v3, v2
	s_waitcnt lgkmcnt(0)
	v_mad_u32_u24 v5, v1, v0, v0
	s_add_u32 s10, s90, 0x494e400
	s_addc_u32 s11, s91, 0
	s_cbranch_vccnz .Lgb_poll
	buffer_wbl2 sc1
	s_waitcnt vmcnt(0)
	v_mov_b32_e32 v2, 1
	global_atomic_add v159, v2, s[10:11]
.Lgb_poll:
	global_load_dword v0, v159, s[10:11] sc1
	s_waitcnt vmcnt(0)
	v_cmp_lt_u32_e32 vcc, v0, v5
	s_cbranch_vccz .Lgb_done
	s_sleep 1
	s_branch .Lgb_poll
.Lgb_done:
	s_movk_i32 s36, 0x7f
